# p@Wp GEMM epilogue: (n=0,n=1) dwordx2 store pairs merged into dwordx4 stores via v_permlane16_swap (4 sites)
# speedup vs baseline: 1.0353x; 1.0072x over previous
.LBB0_819:
	v_lshl_add_u32 v132, s36, 8, v136
	v_lshl_or_b32 v142, s62, 8, v138
	v_ashrrev_i32_e32 v133, 31, v132
	v_ashrrev_i32_e32 v143, 31, v142
	v_lshlrev_b64 v[144:145], 11, v[132:133]
	v_cvt_pk_bf16_f32 v146, v124, v125
	v_cvt_pk_bf16_f32 v147, v126, v127
	v_lshl_add_u64 v[124:125], s[6:7], 0, v[144:145]
	v_lshlrev_b64 v[126:127], 1, v[142:143]
	v_lshl_add_u64 v[124:125], v[124:125], 0, v[126:127]
	v_mov_b32_e32 v148, v146
	v_mov_b32_e32 v149, v147
	v_cvt_pk_bf16_f32 v112, v112, v113
	v_cvt_pk_bf16_f32 v113, v114, v115
	v_mov_b32_e32 v150, v112
	v_mov_b32_e32 v151, v113
	v_bfe_u32 v156, v206, 4, 1
	v_mul_u32_u24_e32 v156, 24, v156
	v_mov_b32_e32 v157, 0
	v_lshl_add_u64 v[158:159], v[124:125], 0, v[156:157]
	v_permlane16_swap_b32_e32 v148, v150
	v_permlane16_swap_b32_e32 v149, v151
	global_store_dwordx4 v[158:159], v[148:151], off
	v_cvt_pk_bf16_f32 v112, v120, v121
	v_cvt_pk_bf16_f32 v113, v122, v123
	v_mov_b32_e32 v152, v112
	v_mov_b32_e32 v153, v113
	v_cvt_pk_bf16_f32 v112, v116, v117
	v_cvt_pk_bf16_f32 v113, v118, v119
	v_mov_b32_e32 v154, v112
	v_mov_b32_e32 v155, v113
	v_bfe_u32 v156, v206, 4, 1
	v_mul_u32_u24_e32 v156, 24, v156
	v_mov_b32_e32 v157, 0
	v_lshl_add_u64 v[158:159], v[124:125], 0, v[156:157]
	v_permlane16_swap_b32_e32 v152, v154
	v_permlane16_swap_b32_e32 v153, v155
	global_store_dwordx4 v[158:159], v[152:155], off offset:256
	v_or_b32_e32 v112, 16, v132
	v_ashrrev_i32_e32 v113, 31, v112
	v_lshlrev_b64 v[112:113], 11, v[112:113]
	v_cvt_pk_bf16_f32 v108, v108, v109
	v_cvt_pk_bf16_f32 v109, v110, v111
	v_lshl_add_u64 v[110:111], s[6:7], 0, v[112:113]
	v_lshl_add_u64 v[110:111], v[110:111], 0, v[126:127]
	v_mov_b32_e32 v148, v108
	v_mov_b32_e32 v149, v109
	v_cvt_pk_bf16_f32 v96, v96, v97
	v_cvt_pk_bf16_f32 v97, v98, v99
	v_mov_b32_e32 v150, v96
	v_mov_b32_e32 v151, v97
	v_bfe_u32 v156, v206, 4, 1
	v_mul_u32_u24_e32 v156, 24, v156
	v_mov_b32_e32 v157, 0
	v_lshl_add_u64 v[158:159], v[110:111], 0, v[156:157]
	v_permlane16_swap_b32_e32 v148, v150
	v_permlane16_swap_b32_e32 v149, v151
	global_store_dwordx4 v[158:159], v[148:151], off
	v_cvt_pk_bf16_f32 v96, v104, v105
	v_cvt_pk_bf16_f32 v97, v106, v107
	v_mov_b32_e32 v152, v96
	v_mov_b32_e32 v153, v97
	v_cvt_pk_bf16_f32 v96, v100, v101
	v_cvt_pk_bf16_f32 v97, v102, v103
	v_mov_b32_e32 v154, v96
	v_mov_b32_e32 v155, v97
	v_bfe_u32 v156, v206, 4, 1
	v_mul_u32_u24_e32 v156, 24, v156
	v_mov_b32_e32 v157, 0
	v_lshl_add_u64 v[158:159], v[110:111], 0, v[156:157]
	v_permlane16_swap_b32_e32 v152, v154
	v_permlane16_swap_b32_e32 v153, v155
	global_store_dwordx4 v[158:159], v[152:155], off offset:256
	v_or_b32_e32 v96, 32, v132
	v_ashrrev_i32_e32 v97, 31, v96
	v_lshlrev_b64 v[96:97], 11, v[96:97]
	v_cvt_pk_bf16_f32 v92, v92, v93
	v_cvt_pk_bf16_f32 v93, v94, v95
	v_lshl_add_u64 v[94:95], s[6:7], 0, v[96:97]
	v_lshl_add_u64 v[94:95], v[94:95], 0, v[126:127]
	v_mov_b32_e32 v148, v92
	v_mov_b32_e32 v149, v93
	v_cvt_pk_bf16_f32 v80, v80, v81
	v_cvt_pk_bf16_f32 v81, v82, v83
	v_mov_b32_e32 v150, v80
	v_mov_b32_e32 v151, v81
	v_bfe_u32 v156, v206, 4, 1
	v_mul_u32_u24_e32 v156, 24, v156
	v_mov_b32_e32 v157, 0
	v_lshl_add_u64 v[158:159], v[94:95], 0, v[156:157]
	v_permlane16_swap_b32_e32 v148, v150
	v_permlane16_swap_b32_e32 v149, v151
	global_store_dwordx4 v[158:159], v[148:151], off
	v_cvt_pk_bf16_f32 v80, v88, v89
	v_cvt_pk_bf16_f32 v81, v90, v91
	v_mov_b32_e32 v152, v80
	v_mov_b32_e32 v153, v81
	v_cvt_pk_bf16_f32 v80, v84, v85
	v_cvt_pk_bf16_f32 v81, v86, v87
	v_mov_b32_e32 v154, v80
	v_mov_b32_e32 v155, v81
	v_bfe_u32 v156, v206, 4, 1
	v_mul_u32_u24_e32 v156, 24, v156
	v_mov_b32_e32 v157, 0
	v_lshl_add_u64 v[158:159], v[94:95], 0, v[156:157]
	v_permlane16_swap_b32_e32 v152, v154
	v_permlane16_swap_b32_e32 v153, v155
	global_store_dwordx4 v[158:159], v[152:155], off offset:256
	v_or_b32_e32 v80, 48, v132
	v_ashrrev_i32_e32 v81, 31, v80
	v_lshlrev_b64 v[80:81], 11, v[80:81]
	v_cvt_pk_bf16_f32 v60, v60, v61
	v_cvt_pk_bf16_f32 v61, v62, v63
	v_lshl_add_u64 v[62:63], s[6:7], 0, v[80:81]
	v_lshl_add_u64 v[62:63], v[62:63], 0, v[126:127]
	v_mov_b32_e32 v148, v60
	v_mov_b32_e32 v149, v61
	v_cvt_pk_bf16_f32 v48, v48, v49
	v_cvt_pk_bf16_f32 v49, v50, v51
	v_mov_b32_e32 v150, v48
	v_mov_b32_e32 v151, v49
	v_bfe_u32 v156, v206, 4, 1
	v_mul_u32_u24_e32 v156, 24, v156
	v_mov_b32_e32 v157, 0
	v_lshl_add_u64 v[158:159], v[62:63], 0, v[156:157]
	v_permlane16_swap_b32_e32 v148, v150
	v_permlane16_swap_b32_e32 v149, v151
	global_store_dwordx4 v[158:159], v[148:151], off
	v_cvt_pk_bf16_f32 v48, v56, v57
	v_cvt_pk_bf16_f32 v49, v58, v59
	v_mov_b32_e32 v152, v48
	v_mov_b32_e32 v153, v49
	v_cvt_pk_bf16_f32 v48, v52, v53
	v_add_co_u32_e32 v52, vcc, s58, v124
	v_cvt_pk_bf16_f32 v49, v54, v55
	v_mov_b32_e32 v154, v48
	v_mov_b32_e32 v155, v49
	v_bfe_u32 v156, v206, 4, 1
	v_mul_u32_u24_e32 v156, 24, v156
	v_mov_b32_e32 v157, 0
	v_lshl_add_u64 v[158:159], v[62:63], 0, v[156:157]
	v_permlane16_swap_b32_e32 v152, v154
	v_permlane16_swap_b32_e32 v153, v155
	global_store_dwordx4 v[158:159], v[152:155], off offset:256
	v_cvt_pk_bf16_f32 v48, v76, v77
	s_nop 0
	v_addc_co_u32_e32 v53, vcc, 0, v125, vcc
	v_cvt_pk_bf16_f32 v49, v78, v79
	v_lshl_add_u64 v[50:51], v[124:125], 0, s[18:19]
	v_mov_b32_e32 v148, v48
	v_mov_b32_e32 v149, v49
	v_cvt_pk_bf16_f32 v48, v64, v65
	v_cvt_pk_bf16_f32 v49, v66, v67
	v_mov_b32_e32 v150, v48
	v_mov_b32_e32 v151, v49
	v_bfe_u32 v156, v206, 4, 1
	v_mul_u32_u24_e32 v156, 24, v156
	v_mov_b32_e32 v157, 0
	v_lshl_add_u64 v[158:159], v[50:51], 0, v[156:157]
	v_permlane16_swap_b32_e32 v148, v150
	v_permlane16_swap_b32_e32 v149, v151
	global_store_dwordx4 v[158:159], v[148:151], off
	v_cvt_pk_bf16_f32 v48, v72, v73
	v_cvt_pk_bf16_f32 v49, v74, v75
	v_mov_b32_e32 v152, v48
	v_mov_b32_e32 v153, v49
	v_cvt_pk_bf16_f32 v48, v68, v69
	v_cvt_pk_bf16_f32 v49, v70, v71
	v_mov_b32_e32 v154, v48
	v_mov_b32_e32 v155, v49
	v_bfe_u32 v156, v206, 4, 1
	v_mul_u32_u24_e32 v156, 24, v156
	v_mov_b32_e32 v157, 0
	v_lshl_add_u64 v[158:159], v[50:51], 0, v[156:157]
	v_permlane16_swap_b32_e32 v152, v154
	v_permlane16_swap_b32_e32 v153, v155
	global_store_dwordx4 v[158:159], v[152:155], off offset:256
	v_add_co_u32_e32 v48, vcc, s59, v124
	v_cvt_pk_bf16_f32 v44, v44, v45
	v_cvt_pk_bf16_f32 v45, v46, v47
	v_lshl_add_u64 v[46:47], v[124:125], 0, s[20:21]
	s_nop 0
	v_addc_co_u32_e32 v49, vcc, 0, v125, vcc
	v_mov_b32_e32 v148, v44
	v_mov_b32_e32 v149, v45
	v_cvt_pk_bf16_f32 v32, v32, v33
	v_cvt_pk_bf16_f32 v33, v34, v35
	v_mov_b32_e32 v150, v32
	v_mov_b32_e32 v151, v33
	v_bfe_u32 v156, v206, 4, 1
	v_mul_u32_u24_e32 v156, 24, v156
	v_mov_b32_e32 v157, 0
	v_lshl_add_u64 v[158:159], v[46:47], 0, v[156:157]
	v_permlane16_swap_b32_e32 v148, v150
	v_permlane16_swap_b32_e32 v149, v151
	global_store_dwordx4 v[158:159], v[148:151], off
	v_cvt_pk_bf16_f32 v32, v40, v41
	v_cvt_pk_bf16_f32 v33, v42, v43
	v_mov_b32_e32 v152, v32
	v_mov_b32_e32 v153, v33
	v_cvt_pk_bf16_f32 v32, v36, v37
	v_cvt_pk_bf16_f32 v33, v38, v39
	v_mov_b32_e32 v154, v32
	v_mov_b32_e32 v155, v33
	v_bfe_u32 v156, v206, 4, 1
	v_mul_u32_u24_e32 v156, 24, v156
	v_mov_b32_e32 v157, 0
	v_lshl_add_u64 v[158:159], v[46:47], 0, v[156:157]
	v_permlane16_swap_b32_e32 v152, v154
	v_permlane16_swap_b32_e32 v153, v155
	global_store_dwordx4 v[158:159], v[152:155], off offset:256
	v_add_co_u32_e32 v32, vcc, s60, v124
	v_cvt_pk_bf16_f32 v28, v28, v29
	v_cvt_pk_bf16_f32 v29, v30, v31
	v_lshl_add_u64 v[30:31], v[124:125], 0, s[22:23]
	s_nop 0
	v_addc_co_u32_e32 v33, vcc, 0, v125, vcc
	v_mov_b32_e32 v148, v28
	v_mov_b32_e32 v149, v29
	v_cvt_pk_bf16_f32 v16, v16, v17
	v_cvt_pk_bf16_f32 v17, v18, v19
	v_mov_b32_e32 v150, v16
	v_mov_b32_e32 v151, v17
	v_bfe_u32 v156, v206, 4, 1
	v_mul_u32_u24_e32 v156, 24, v156
	v_mov_b32_e32 v157, 0
	v_lshl_add_u64 v[158:159], v[30:31], 0, v[156:157]
	v_permlane16_swap_b32_e32 v148, v150
	v_permlane16_swap_b32_e32 v149, v151
	global_store_dwordx4 v[158:159], v[148:151], off
	v_cvt_pk_bf16_f32 v16, v24, v25
	v_cvt_pk_bf16_f32 v17, v26, v27
	v_mov_b32_e32 v152, v16
	v_mov_b32_e32 v153, v17
	v_cvt_pk_bf16_f32 v16, v20, v21
	v_cvt_pk_bf16_f32 v17, v22, v23
	v_mov_b32_e32 v154, v16
	v_mov_b32_e32 v155, v17
	v_bfe_u32 v156, v206, 4, 1
	v_mul_u32_u24_e32 v156, 24, v156
	v_mov_b32_e32 v157, 0
	v_lshl_add_u64 v[158:159], v[30:31], 0, v[156:157]
	v_permlane16_swap_b32_e32 v152, v154
	v_permlane16_swap_b32_e32 v153, v155
	global_store_dwordx4 v[158:159], v[152:155], off offset:256
	v_add_co_u32_e32 v16, vcc, s61, v124
	v_cvt_pk_bf16_f32 v12, v12, v13
	v_cvt_pk_bf16_f32 v13, v14, v15
	v_lshl_add_u64 v[14:15], v[124:125], 0, s[24:25]
	s_nop 0
	v_addc_co_u32_e32 v17, vcc, 0, v125, vcc
	v_mov_b32_e32 v148, v12
	v_mov_b32_e32 v149, v13
	v_cvt_pk_bf16_f32 v0, v0, v1
	v_cvt_pk_bf16_f32 v1, v2, v3
	v_mov_b32_e32 v150, v0
	v_mov_b32_e32 v151, v1
	v_bfe_u32 v156, v206, 4, 1
	v_mul_u32_u24_e32 v156, 24, v156
	v_mov_b32_e32 v157, 0
	v_lshl_add_u64 v[158:159], v[14:15], 0, v[156:157]
	v_permlane16_swap_b32_e32 v148, v150
	v_permlane16_swap_b32_e32 v149, v151
	global_store_dwordx4 v[158:159], v[148:151], off
	v_cvt_pk_bf16_f32 v0, v8, v9
	v_cvt_pk_bf16_f32 v1, v10, v11
	s_andn2_b64 vcc, exec, s[4:5]
	s_mov_b64 s[4:5], -1
	v_mov_b32_e32 v152, v0
	v_mov_b32_e32 v153, v1
	v_cvt_pk_bf16_f32 v0, v4, v5
	v_cvt_pk_bf16_f32 v1, v6, v7
	v_mov_b32_e32 v154, v0
	v_mov_b32_e32 v155, v1
	v_bfe_u32 v156, v206, 4, 1
	v_mul_u32_u24_e32 v156, 24, v156
	v_mov_b32_e32 v157, 0
	v_lshl_add_u64 v[158:159], v[14:15], 0, v[156:157]
	v_permlane16_swap_b32_e32 v152, v154
	v_permlane16_swap_b32_e32 v153, v155
	global_store_dwordx4 v[158:159], v[152:155], off offset:256
	s_cbranch_vccnz .LBB0_810
	s_andn2_b64 vcc, exec, s[2:3]
	s_cbranch_vccnz .LBB0_809
	s_barrier
	s_branch .LBB0_809
